# v24 plus K fragments double-buffered in registers during QK^T (two read pairs in flight)
# baseline (speedup 1.0000x reference)
; #define SBAR() __builtin_amdgcn_sched_barrier(0)
; __device__ __forceinline__ void finishSM(f32x16& p0, f32x16& p1, float alpha, float& l_reg, bf16x8& pa0, bf16x8& pa1, bf16x8& pa2, bf16x8& pa3) {
; #pragma unroll
;   for (int r = 0; r < 16; ++r) p1[r] = __builtin_amdgcn_exp2f(p1[r]);
;   float ps = 0;
; #pragma unroll
;   for (int r = 0; r < 16; ++r) ps += p0[r];
; #pragma unroll
;   for (int r = 0; r < 16; ++r) ps += p1[r];
;   { auto rr = __builtin_amdgcn_permlane32_swap(__float_as_uint(ps), __float_as_uint(ps), false, false);
;     ps = __uint_as_float(rr[0]) + __uint_as_float(rr[1]); }
;   l_reg = l_reg * alpha + ps;
;     ...
;   PK4(p0, 0, pa0); PK4(p0, 8, pa1); PK4(p1, 0, pa2); PK4(p1, 8, pa3);
;     ...
; }
; __device__ __forceinline__ void qkt(f32x16& p0, f32x16& p1, const bf16_t* Ks, const bf16x8* qr, int r32, int hi) {
;   p0 = f32x16{}; p1 = f32x16{};
; #pragma unroll
;   for (int d0 = 0; d0 < 8; ++d0) { int cb = (d0 * 16 + hi * 8) * 2;
;     bf16x8 b0 = *reinterpret_cast<const bf16x8*>((const char*)Ks + KSWZ(r32, cb));
;     bf16x8 b1 = *reinterpret_cast<const bf16x8*>((const char*)Ks + KSWZ(32 + r32, cb));
;     p0 = __builtin_amdgcn_mfma_f32_32x32x16_bf16(b0, qr[d0], p0, 0, 0, 0);
;     p1 = __builtin_amdgcn_mfma_f32_32x32x16_bf16(b1, qr[d0], p1, 0, 0, 0); }
; __device__ __forceinline__ void attn_body(const bf16_t* __restrict__ Qb, const bf16_t* __restrict__ Kh, const bf16_t* __restrict__ Vh,
;                                           bf16_t* __restrict__ Ob, const bf16_t* __restrict__ AGb, int seq, char* lds) {
;     ...
;     SBAR(); qkt(pB0, pB1, (bf16_t*)((char*)K_lds + SHM_K), qr, r32, hi);
;     finishSM(pA0, pA1, alA, l_reg, pa0, pa1, pa2, pa3); SBAR();
.LBB0_199:
	ds_read_b128 v[64:67], v206 offset:49152
	ds_read_b128 v[68:71], v206 offset:57344
	ds_read_b128 v[216:219], v211 offset:49152
	ds_read_b128 v[220:223], v211 offset:57344
	ds_read_b128 v[248:251], v210 offset:49152
	ds_read_b128 v[252:255], v210 offset:57344
	v_add_f32_e32 v162, 0, v163
	v_add_f32_e32 v162, v177, v162
	s_waitcnt lgkmcnt(5)
	v_mfma_f32_32x32x16_bf16 v[80:95], v[64:67], v[118:121], 0
	v_add_f32_e32 v162, v164, v162
	v_add_f32_e32 v162, v186, v162
	v_add_f32_e32 v162, v176, v162
	v_add_f32_e32 v162, v187, v162
	v_add_f32_e32 v162, v165, v162
	v_add_f32_e32 v162, v175, v162
	v_add_f32_e32 v162, v166, v162
	s_waitcnt lgkmcnt(4)
	v_mfma_f32_32x32x16_bf16 v[64:79], v[68:71], v[118:121], 0
	v_add_f32_e32 v162, v173, v162
	v_add_f32_e32 v162, v167, v162
	v_add_f32_e32 v162, v174, v162
	v_exp_f32_e32 v160, v160
	v_add_f32_e32 v162, v168, v162
	v_exp_f32_e32 v161, v161
	v_add_f32_e32 v162, v171, v162
	s_waitcnt lgkmcnt(3)
	v_mfma_f32_32x32x16_bf16 v[80:95], v[216:219], v[114:117], v[80:95]
	v_exp_f32_e32 v158, v158
	v_add_f32_e32 v162, v169, v162
	v_exp_f32_e32 v159, v159
	v_add_f32_e32 v162, v172, v162
	v_exp_f32_e32 v154, v154
	v_add_f32_e32 v162, v160, v162
	v_exp_f32_e32 v155, v155
	s_waitcnt lgkmcnt(2)
	v_mfma_f32_32x32x16_bf16 v[64:79], v[220:223], v[114:117], v[64:79]
	ds_read_b128 v[216:219], v209 offset:49152
	ds_read_b128 v[220:223], v209 offset:57344
	v_add_f32_e32 v162, v161, v162
	v_exp_f32_e32 v150, v150
	v_add_f32_e32 v162, v158, v162
	v_exp_f32_e32 v151, v151
	v_add_f32_e32 v162, v159, v162
	v_exp_f32_e32 v148, v148
	s_waitcnt lgkmcnt(3)
	v_mfma_f32_32x32x16_bf16 v[80:95], v[248:251], v[126:129], v[80:95]
	v_add_f32_e32 v162, v154, v162
	v_exp_f32_e32 v149, v149
	v_add_f32_e32 v162, v155, v162
	v_exp_f32_e32 v156, v156
	v_add_f32_e32 v162, v150, v162
	v_exp_f32_e32 v157, v157
	v_add_f32_e32 v162, v151, v162
	s_waitcnt lgkmcnt(2)
	v_mfma_f32_32x32x16_bf16 v[64:79], v[252:255], v[126:129], v[64:79]
	ds_read_b128 v[248:251], v208 offset:49152
	ds_read_b128 v[252:255], v208 offset:57344
	v_exp_f32_e32 v152, v152
	v_add_f32_e32 v162, v148, v162
	v_exp_f32_e32 v153, v153
	v_add_f32_e32 v162, v149, v162
	v_exp_f32_e32 v146, v146
	v_add_f32_e32 v162, v156, v162
	s_waitcnt lgkmcnt(3)
	v_mfma_f32_32x32x16_bf16 v[80:95], v[216:219], v[122:125], v[80:95]
	v_exp_f32_e32 v147, v147
	v_add_f32_e32 v162, v157, v162
	v_add_f32_e32 v162, v152, v162
	v_add_f32_e32 v162, v153, v162
	v_add_f32_e32 v162, v146, v162
	v_add_f32_e32 v215, v147, v162
	s_waitcnt lgkmcnt(2)
	v_mfma_f32_32x32x16_bf16 v[64:79], v[220:223], v[122:125], v[64:79]
	ds_read_b128 v[216:219], v207 offset:49152
	ds_read_b128 v[220:223], v207 offset:57344
	s_waitcnt lgkmcnt(3)
	v_mfma_f32_32x32x16_bf16 v[80:95], v[248:251], v[110:113], v[80:95]
	s_waitcnt lgkmcnt(2)
	v_mfma_f32_32x32x16_bf16 v[64:79], v[252:255], v[110:113], v[64:79]
	ds_read_b128 v[248:251], v213 offset:49152
	ds_read_b128 v[252:255], v213 offset:57344
	s_waitcnt lgkmcnt(3)
	v_mfma_f32_32x32x16_bf16 v[80:95], v[216:219], v[106:109], v[80:95]
	s_waitcnt lgkmcnt(2)
	v_mfma_f32_32x32x16_bf16 v[64:79], v[220:223], v[106:109], v[64:79]
	ds_read_b128 v[216:219], v212 offset:49152
	ds_read_b128 v[220:223], v212 offset:57344
	s_waitcnt lgkmcnt(3)
	v_mfma_f32_32x32x16_bf16 v[80:95], v[248:251], v[102:105], v[80:95]
	s_waitcnt lgkmcnt(2)
	v_mfma_f32_32x32x16_bf16 v[64:79], v[252:255], v[102:105], v[64:79]
	v_cvt_pk_bf16_f32 v162, v163, v177
	v_cvt_pk_bf16_f32 v163, v164, v186
	v_cvt_pk_bf16_f32 v164, v176, v187
	v_cvt_pk_bf16_f32 v165, v165, v175
	v_cvt_pk_bf16_f32 v166, v166, v173
	v_cvt_pk_bf16_f32 v167, v167, v174
	s_waitcnt lgkmcnt(1)
	v_mfma_f32_32x32x16_bf16 v[80:95], v[216:219], v[98:101], v[80:95]
	v_mov_b32_e32 v216, v215
	s_nop 1
	v_permlane32_swap_b32_e32 v215, v216
	v_permlane32_swap_b32_e32 v162, v164
	v_cvt_pk_bf16_f32 v168, v168, v171
	v_cvt_pk_bf16_f32 v169, v169, v172
	s_waitcnt lgkmcnt(0)
	v_mfma_f32_32x32x16_bf16 v[64:79], v[220:223], v[98:101], v[64:79]
	ds_read_b64_tr_b16 v[222:223], v201 offset:0
	ds_read_b64_tr_b16 v[224:225], v201 offset:0x800
	ds_read_b64_tr_b16 v[226:227], v201 offset:0x1000
	ds_read_b64_tr_b16 v[228:229], v201 offset:0x1800
	ds_read_b64_tr_b16 v[230:231], v201 offset:0x2000
	ds_read_b64_tr_b16 v[232:233], v201 offset:0x2800
	ds_read_b64_tr_b16 v[234:235], v201 offset:0x3000
	ds_read_b64_tr_b16 v[236:237], v201 offset:0x3800
	v_cvt_pk_bf16_f32 v172, v160, v161
	v_cvt_pk_bf16_f32 v173, v158, v159
	v_cvt_pk_bf16_f32 v174, v154, v155
	v_cvt_pk_bf16_f32 v175, v150, v151
	v_cvt_pk_bf16_f32 v218, v148, v149
	v_cvt_pk_bf16_f32 v219, v156, v157
	v_cvt_pk_bf16_f32 v220, v152, v153
	v_cvt_pk_bf16_f32 v221, v146, v147
	v_permlane32_swap_b32_e32 v163, v165
	v_permlane32_swap_b32_e32 v166, v168
	v_permlane32_swap_b32_e32 v167, v169
	v_permlane32_swap_b32_e32 v172, v174
	v_permlane32_swap_b32_e32 v173, v175
	v_permlane32_swap_b32_e32 v218, v220
	v_permlane32_swap_b32_e32 v219, v221
	v_lshl_add_u64 v[188:189], s[20:21], 0, v[96:97]
	v_add_co_u32_e32 v146, vcc, s63, v188
	v_lshl_add_u64 v[186:187], s[20:21], 0, v[184:185]
	s_nop 0
	v_addc_co_u32_e32 v147, vcc, 0, v189, vcc
	v_add_co_u32_e32 v150, vcc, s63, v186
	s_nop 1
	v_addc_co_u32_e32 v151, vcc, 0, v187, vcc
	v_add_co_u32_e32 v154, vcc, s90, v188
	global_load_dwordx4 v[146:149], v[146:147], off
	s_nop 0
	global_load_dwordx4 v[150:153], v[150:151], off
	v_addc_co_u32_e32 v155, vcc, 0, v189, vcc
	v_add_co_u32_e32 v158, vcc, s90, v186
	s_nop 1
	v_addc_co_u32_e32 v159, vcc, 0, v187, vcc
	global_load_dwordx4 v[154:157], v[154:155], off
	s_nop 0
	global_load_dwordx4 v[158:161], v[158:159], off
	s_waitcnt lgkmcnt(0)
; #define SBAR() __builtin_amdgcn_sched_barrier(0)
; #define SWRITE(b, i) do { *(bf16x8*)((char*)V_lds + (b) * SHM_V + vst0) = sr_[i].vs0;          \
;     *(bf16x8*)((char*)V_lds + (b) * SHM_V + vst1) = sr_[i].vs1; int kc = sc * 2;               \
;     *(bf16x8*)((char*)K_lds + (b) * SHM_K + KSWZ(sr, kc)) = sr_[i].ks0;                       \
;     *(bf16x8*)((char*)K_lds + (b) * SHM_K + KSWZ(32 + sr, kc)) = sr_[i].ks1; } while (0)
; #define SWAIT() asm volatile("s_waitcnt vmcnt(4)" ::: "memory")
; #define RESC(a) do { if (__any((a) < 1.f)) { if (hi == 0) al_l[r32] = (a); asm volatile("s_waitcnt lgkmcnt(0)" ::: "memory"); \
;     _Pragma("unroll") for (int d = 0; d < 4; ++d) _Pragma("unroll") for (int r = 0; r < 16; ++r) o[d][r] *= al_l[crow(r, hi)]; } } while (0)
; template <int D0> __device__ __forceinline__ void pv_one(f32x16& od, int vb, bf16x8 pa0, bf16x8 pa1, bf16x8 pa2, bf16x8 pa3) {
;   const s16x4 l0 = tr_read<v_rd_off(D0, 0, 0)>(vb), h0 = tr_read<v_rd_off(D0, 0, 1)>(vb), l1 = tr_read<v_rd_off(D0, 1, 0)>(vb), h1 = tr_read<v_rd_off(D0, 1, 1)>(vb);
;   const s16x4 l2 = tr_read<v_rd_off(D0, 2, 0)>(vb), h2 = tr_read<v_rd_off(D0, 2, 1)>(vb), l3 = tr_read<v_rd_off(D0, 3, 0)>(vb), h3 = tr_read<v_rd_off(D0, 3, 1)>(vb);
;   asm volatile("s_waitcnt lgkmcnt(0)" ::: "memory"); SBAR();
;     ...
;   od = __builtin_amdgcn_mfma_f32_32x32x16_bf16(pa0, PK(l0, h0), od, 0, 0, 0);
;   od = __builtin_amdgcn_mfma_f32_32x32x16_bf16(pa1, PK(l1, h1), od, 0, 0, 0);
;   od = __builtin_amdgcn_mfma_f32_32x32x16_bf16(pa2, PK(l2, h2), od, 0, 0, 0);
;   od = __builtin_amdgcn_mfma_f32_32x32x16_bf16(pa3, PK(l3, h3), od, 0, 0, 0);
;     ...
; }
; __device__ __forceinline__ void pv_d0(f32x16* o, int vb, bf16x8 pa0, bf16x8 pa1, bf16x8 pa2, bf16x8 pa3) {
;   pv_one<0>(o[0], vb, pa0, pa1, pa2, pa3); pv_one<1>(o[1], vb, pa0, pa1, pa2, pa3); pv_one<2>(o[2], vb, pa0, pa1, pa2, pa3); pv_one<3>(o[3], vb, pa0, pa1, pa2, pa3);
; }
; __device__ __forceinline__ void attn_body(const bf16_t* __restrict__ Qb, const bf16_t* __restrict__ Kh, const bf16_t* __restrict__ Vh,
;                                           bf16_t* __restrict__ Ob, const bf16_t* __restrict__ AGb, int seq, char* lds) {
;     ...
;     pv_d0(o, vb0, pa0, pa1, pa2, pa3); partialSM(pB0, pB1, m_reg, mnB, alB);
;     __syncthreads(); SWAIT(); SWRITE(0, SE);
;     RESC(alB); __syncthreads();
	s_nop 0
	v_mfma_f32_32x32x16_bf16 v[0:15], v[162:165], v[222:225], v[0:15]
	ds_read_b64_tr_b16 v[222:223], v201 offset:0x200
	ds_read_b64_tr_b16 v[224:225], v201 offset:0xa00
	v_mfma_f32_32x32x16_bf16 v[0:15], v[166:169], v[226:229], v[0:15]
	ds_read_b64_tr_b16 v[226:227], v201 offset:0x1200
	ds_read_b64_tr_b16 v[228:229], v201 offset:0x1a00
	v_mfma_f32_32x32x16_bf16 v[0:15], v[172:175], v[230:233], v[0:15]
	ds_read_b64_tr_b16 v[230:231], v201 offset:0x2200
	ds_read_b64_tr_b16 v[232:233], v201 offset:0x2a00
	v_mfma_f32_32x32x16_bf16 v[0:15], v[218:221], v[234:237], v[0:15]
	ds_read_b64_tr_b16 v[234:235], v201 offset:0x3200
	ds_read_b64_tr_b16 v[236:237], v201 offset:0x3a00
	s_waitcnt lgkmcnt(0)
	v_mfma_f32_32x32x16_bf16 v[48:63], v[162:165], v[222:225], v[48:63]
	ds_read_b64_tr_b16 v[222:223], v201 offset:0x400
	ds_read_b64_tr_b16 v[224:225], v201 offset:0xc00
	v_mfma_f32_32x32x16_bf16 v[48:63], v[166:169], v[226:229], v[48:63]
	ds_read_b64_tr_b16 v[226:227], v201 offset:0x1400
	ds_read_b64_tr_b16 v[228:229], v201 offset:0x1c00
	v_mfma_f32_32x32x16_bf16 v[48:63], v[172:175], v[230:233], v[48:63]
	ds_read_b64_tr_b16 v[230:231], v201 offset:0x2400
	ds_read_b64_tr_b16 v[232:233], v201 offset:0x2c00
	v_mfma_f32_32x32x16_bf16 v[48:63], v[218:221], v[234:237], v[48:63]
	ds_read_b64_tr_b16 v[234:235], v201 offset:0x3400
	ds_read_b64_tr_b16 v[236:237], v201 offset:0x3c00
	s_waitcnt lgkmcnt(0)
	v_mfma_f32_32x32x16_bf16 v[32:47], v[162:165], v[222:225], v[32:47]
	ds_read_b64_tr_b16 v[222:223], v201 offset:0x600
	ds_read_b64_tr_b16 v[224:225], v201 offset:0xe00
	v_mfma_f32_32x32x16_bf16 v[32:47], v[166:169], v[226:229], v[32:47]
	ds_read_b64_tr_b16 v[226:227], v201 offset:0x1600
	ds_read_b64_tr_b16 v[228:229], v201 offset:0x1e00
	v_mfma_f32_32x32x16_bf16 v[32:47], v[172:175], v[230:233], v[32:47]
	ds_read_b64_tr_b16 v[230:231], v201 offset:0x2600
	ds_read_b64_tr_b16 v[232:233], v201 offset:0x2e00
	v_mfma_f32_32x32x16_bf16 v[32:47], v[218:221], v[234:237], v[32:47]
	ds_read_b64_tr_b16 v[234:235], v201 offset:0x3600
	ds_read_b64_tr_b16 v[236:237], v201 offset:0x3e00
	s_waitcnt lgkmcnt(0)
	v_mfma_f32_32x32x16_bf16 v[16:31], v[162:165], v[222:225], v[16:31]
	v_max_f32_e32 v162, v81, v81
	v_max_f32_e32 v163, v80, v80
	v_max_f32_e32 v162, v163, v162
	v_max3_f32 v162, v162, v82, v83
	v_max3_f32 v162, v162, v84, v85
	v_max3_f32 v162, v162, v86, v87
	v_max3_f32 v162, v162, v88, v89
	v_max3_f32 v162, v162, v90, v91
	v_max3_f32 v162, v162, v92, v93
	v_mfma_f32_32x32x16_bf16 v[16:31], v[166:169], v[226:229], v[16:31]
	v_max3_f32 v162, v162, v94, v95
	v_max3_f32 v162, v162, v64, v65
	v_max3_f32 v162, v162, v66, v67
	v_max3_f32 v162, v162, v68, v69
	v_max3_f32 v162, v162, v70, v71
	v_max3_f32 v162, v162, v72, v73
	v_max3_f32 v162, v162, v74, v75
	v_max3_f32 v162, v162, v76, v77
	v_mfma_f32_32x32x16_bf16 v[16:31], v[172:175], v[230:233], v[16:31]
	v_max3_f32 v162, v162, v78, v79
	v_mov_b32_e32 v163, v162
	s_nop 1
	v_permlane32_swap_b32_e32 v162, v163
	v_max_f32_e32 v163, v163, v163
	v_max_f32_e32 v162, v162, v162
	v_max_f32_e32 v162, v162, v163
	v_sub_f32_e32 v163, v162, v170
	v_cmp_ge_f32_e32 vcc, s62, v163
	v_max_f32_e32 v163, v170, v170
	v_max_f32_e32 v162, v163, v162
	v_mfma_f32_32x32x16_bf16 v[16:31], v[218:221], v[234:237], v[16:31]
	v_sub_f32_e32 v163, v170, v162
	v_mul_f32_e32 v163, 0x3e0293ee, v163
	v_exp_f32_e32 v163, v163
	s_cmp_eq_u64 vcc, exec
	s_cselect_b64 s[0:1], -1, 0
	s_waitcnt lgkmcnt(0)
	s_barrier
	s_waitcnt vmcnt(4)
	v_cndmask_b32_e64 v217, v163, 1.0, s[0:1]
	v_cmp_gt_f32_e32 vcc, 1.0, v217
	ds_write_b128 v204, v[130:133]
	ds_write_b128 v205, v[134:137]
	ds_write_b128 v202, v[138:141] offset:32768
	ds_write_b128 v203, v[142:145] offset:32768
	s_cbranch_vccz .LBB0_203
	s_and_saveexec_b64 s[22:23], s[4:5]
	ds_write_b32 v183, v217 offset:128
	s_or_b64 exec, exec, s[22:23]
	s_waitcnt lgkmcnt(0)
	v_add_u32_e32 v163, v181, v180
	ds_read_b128 v[164:167], v163 offset:224
	ds_read_b128 v[172:175], v163 offset:192
	ds_read_b128 v[218:221], v163 offset:160
	ds_read_b128 v[222:225], v163 offset:128
	s_waitcnt lgkmcnt(0)
	v_pk_mul_f32 v[12:13], v[12:13], v[164:165]
	v_pk_mul_f32 v[8:9], v[8:9], v[172:173]
	v_pk_mul_f32 v[4:5], v[4:5], v[218:219]
	v_pk_mul_f32 v[14:15], v[14:15], v[166:167]
	v_pk_mul_f32 v[10:11], v[10:11], v[174:175]
	v_pk_mul_f32 v[6:7], v[6:7], v[220:221]
	v_pk_mul_f32 v[2:3], v[2:3], v[224:225]
	v_pk_mul_f32 v[0:1], v[0:1], v[222:223]
	v_pk_mul_f32 v[60:61], v[60:61], v[164:165]
	v_pk_mul_f32 v[56:57], v[56:57], v[172:173]
	v_pk_mul_f32 v[52:53], v[52:53], v[218:219]
	v_pk_mul_f32 v[62:63], v[62:63], v[166:167]
	v_pk_mul_f32 v[58:59], v[58:59], v[174:175]
	v_pk_mul_f32 v[54:55], v[54:55], v[220:221]
	v_pk_mul_f32 v[50:51], v[50:51], v[224:225]
	v_pk_mul_f32 v[48:49], v[48:49], v[222:223]
	v_pk_mul_f32 v[44:45], v[44:45], v[164:165]
	v_pk_mul_f32 v[40:41], v[40:41], v[172:173]
	v_pk_mul_f32 v[36:37], v[36:37], v[218:219]
	v_pk_mul_f32 v[46:47], v[46:47], v[166:167]
	v_pk_mul_f32 v[42:43], v[42:43], v[174:175]
	v_pk_mul_f32 v[38:39], v[38:39], v[220:221]
	v_pk_mul_f32 v[34:35], v[34:35], v[224:225]
	v_pk_mul_f32 v[32:33], v[32:33], v[222:223]
	v_pk_mul_f32 v[28:29], v[28:29], v[164:165]
	v_pk_mul_f32 v[24:25], v[24:25], v[172:173]
	v_pk_mul_f32 v[20:21], v[20:21], v[218:219]
	v_pk_mul_f32 v[30:31], v[30:31], v[166:167]
	v_pk_mul_f32 v[26:27], v[26:27], v[174:175]
	v_pk_mul_f32 v[22:23], v[22:23], v[220:221]
	v_pk_mul_f32 v[18:19], v[18:19], v[224:225]
	v_pk_mul_f32 v[16:17], v[16:17], v[222:223]
; #define SBAR() __builtin_amdgcn_sched_barrier(0)
; __device__ __forceinline__ void qkt(f32x16& p0, f32x16& p1, const bf16_t* Ks, const bf16x8* qr, int r32, int hi) {
;   p0 = f32x16{}; p1 = f32x16{};
; #pragma unroll
;   for (int d0 = 0; d0 < 8; ++d0) { int cb = (d0 * 16 + hi * 8) * 2;
;     bf16x8 b0 = *reinterpret_cast<const bf16x8*>((const char*)Ks + KSWZ(r32, cb));
;     bf16x8 b1 = *reinterpret_cast<const bf16x8*>((const char*)Ks + KSWZ(32 + r32, cb));
;     p0 = __builtin_amdgcn_mfma_f32_32x32x16_bf16(b0, qr[d0], p0, 0, 0, 0);
;     p1 = __builtin_amdgcn_mfma_f32_32x32x16_bf16(b1, qr[d0], p1, 0, 0, 0); }
; __device__ __forceinline__ void attn_body(const bf16_t* __restrict__ Qb, const bf16_t* __restrict__ Kh, const bf16_t* __restrict__ Vh,
;                                           bf16_t* __restrict__ Ob, const bf16_t* __restrict__ AGb, int seq, char* lds) {
;     ...
;     SBAR(); qkt(pA0, pA1, K_lds, qr, r32, hi);
;     finishSM(pB0, pB1, alB, l_reg, pa0, pa1, pa2, pa3); SBAR();
.LBB0_203:
	v_cndmask_b32_e64 v218, v162, v170, s[0:1]
	v_mul_f32_e32 v219, 0xbe0293ee, v218
	v_fmamk_f32 v80, v80, 0x3e0293ee, v219
	v_fmamk_f32 v81, v81, 0x3e0293ee, v219
	v_fmamk_f32 v82, v82, 0x3e0293ee, v219
	v_fmamk_f32 v83, v83, 0x3e0293ee, v219
	v_fmamk_f32 v84, v84, 0x3e0293ee, v219
	v_fmamk_f32 v85, v85, 0x3e0293ee, v219
	v_fmamk_f32 v86, v86, 0x3e0293ee, v219
	v_fmamk_f32 v87, v87, 0x3e0293ee, v219
	v_fmamk_f32 v88, v88, 0x3e0293ee, v219
	v_fmamk_f32 v89, v89, 0x3e0293ee, v219
	v_fmamk_f32 v90, v90, 0x3e0293ee, v219
	v_fmamk_f32 v91, v91, 0x3e0293ee, v219
	v_fmamk_f32 v92, v92, 0x3e0293ee, v219
	v_fmamk_f32 v93, v93, 0x3e0293ee, v219
	v_fmamk_f32 v94, v94, 0x3e0293ee, v219
	v_fmamk_f32 v95, v95, 0x3e0293ee, v219
	v_exp_f32_e32 v162, v80
	v_exp_f32_e32 v177, v81
	v_exp_f32_e32 v163, v82
	v_exp_f32_e32 v176, v83
	v_exp_f32_e32 v164, v84
	v_exp_f32_e32 v175, v85
	v_exp_f32_e32 v165, v86
	v_exp_f32_e32 v174, v87
	v_exp_f32_e32 v166, v88
	v_exp_f32_e32 v173, v89
	v_exp_f32_e32 v167, v90
	v_exp_f32_e32 v172, v91
	v_exp_f32_e32 v168, v92
	v_exp_f32_e32 v171, v93
	v_exp_f32_e32 v169, v94
	v_exp_f32_e32 v170, v95
	v_fmamk_f32 v228, v64, 0x3e0293ee, v219
	v_fmamk_f32 v229, v65, 0x3e0293ee, v219
	v_fmamk_f32 v230, v66, 0x3e0293ee, v219
	v_fmamk_f32 v231, v67, 0x3e0293ee, v219
	v_fmamk_f32 v232, v68, 0x3e0293ee, v219
	v_fmamk_f32 v221, v69, 0x3e0293ee, v219
	v_fmamk_f32 v222, v70, 0x3e0293ee, v219
	v_fmamk_f32 v223, v71, 0x3e0293ee, v219
	v_fmamk_f32 v224, v72, 0x3e0293ee, v219
	v_fmamk_f32 v225, v73, 0x3e0293ee, v219
	v_fmamk_f32 v226, v74, 0x3e0293ee, v219
	v_fmamk_f32 v227, v75, 0x3e0293ee, v219
	v_fmamk_f32 v220, v76, 0x3e0293ee, v219
	v_fmamk_f32 v233, v77, 0x3e0293ee, v219
	v_fmamk_f32 v234, v78, 0x3e0293ee, v219
	v_fmac_f32_e32 v219, 0x3e0293ee, v79
	s_waitcnt lgkmcnt(0)
	s_barrier
	ds_read_b128 v[64:67], v206 offset:32768
	ds_read_b128 v[68:71], v206 offset:40960
	ds_read_b128 v[236:239], v211 offset:32768
	ds_read_b128 v[240:243], v211 offset:40960
	ds_read_b128 v[248:251], v210 offset:32768
	ds_read_b128 v[252:255], v210 offset:40960
	v_exp_f32_e32 v228, v228
	v_exp_f32_e32 v229, v229
	s_waitcnt lgkmcnt(2)
	v_mfma_f32_32x32x16_bf16 v[80:95], v[64:67], v[118:121], 0
	v_exp_f32_e32 v230, v230
	v_exp_f32_e32 v231, v231
	v_exp_f32_e32 v232, v232
	v_exp_f32_e32 v221, v221
	v_exp_f32_e32 v222, v222
	v_exp_f32_e32 v223, v223
	v_exp_f32_e32 v224, v224
	v_mfma_f32_32x32x16_bf16 v[64:79], v[68:71], v[118:121], 0
	v_exp_f32_e32 v225, v225
	v_exp_f32_e32 v226, v226
	v_exp_f32_e32 v227, v227
	v_exp_f32_e32 v235, v220
	v_exp_f32_e32 v233, v233
	v_exp_f32_e32 v234, v234
	v_mfma_f32_32x32x16_bf16 v[80:95], v[236:239], v[114:117], v[80:95]
	v_mfma_f32_32x32x16_bf16 v[64:79], v[240:243], v[114:117], v[64:79]
	ds_read_b128 v[236:239], v209 offset:32768
	ds_read_b128 v[240:243], v209 offset:40960
	s_waitcnt lgkmcnt(2)
	v_mfma_f32_32x32x16_bf16 v[80:95], v[248:251], v[126:129], v[80:95]
	v_mfma_f32_32x32x16_bf16 v[64:79], v[252:255], v[126:129], v[64:79]
	ds_read_b128 v[248:251], v208 offset:32768
	ds_read_b128 v[252:255], v208 offset:40960
	s_waitcnt lgkmcnt(2)
	v_mfma_f32_32x32x16_bf16 v[80:95], v[236:239], v[122:125], v[80:95]
	v_mfma_f32_32x32x16_bf16 v[64:79], v[240:243], v[122:125], v[64:79]
	ds_read_b128 v[236:239], v207 offset:32768
	ds_read_b128 v[240:243], v207 offset:40960
	s_waitcnt lgkmcnt(2)
	v_mfma_f32_32x32x16_bf16 v[80:95], v[248:251], v[110:113], v[80:95]
	v_mfma_f32_32x32x16_bf16 v[64:79], v[252:255], v[110:113], v[64:79]
	ds_read_b128 v[248:251], v213 offset:32768
	ds_read_b128 v[252:255], v213 offset:40960
	s_waitcnt lgkmcnt(2)
	v_mfma_f32_32x32x16_bf16 v[80:95], v[236:239], v[106:109], v[80:95]
	v_mfma_f32_32x32x16_bf16 v[64:79], v[240:243], v[106:109], v[64:79]
	ds_read_b128 v[236:239], v212 offset:32768
	ds_read_b128 v[240:243], v212 offset:40960
	s_waitcnt lgkmcnt(2)
	v_mfma_f32_32x32x16_bf16 v[80:95], v[248:251], v[102:105], v[80:95]
	v_mfma_f32_32x32x16_bf16 v[64:79], v[252:255], v[102:105], v[64:79]
	s_waitcnt lgkmcnt(0)
	v_mfma_f32_32x32x16_bf16 v[80:95], v[236:239], v[98:101], v[80:95]
	v_exp_f32_e32 v236, v219
	v_add_f32_e32 v219, 0, v162
	v_add_f32_e32 v219, v177, v219
	v_add_f32_e32 v219, v163, v219
	v_add_f32_e32 v219, v176, v219
	v_add_f32_e32 v219, v164, v219
	v_add_f32_e32 v219, v175, v219
	v_add_f32_e32 v219, v165, v219
	v_add_f32_e32 v219, v174, v219
	v_add_f32_e32 v219, v166, v219
	v_add_f32_e32 v219, v173, v219
	v_add_f32_e32 v219, v167, v219
	v_add_f32_e32 v219, v172, v219
	v_add_f32_e32 v219, v168, v219
	v_add_f32_e32 v219, v171, v219
	v_add_f32_e32 v219, v169, v219
	v_add_f32_e32 v219, v170, v219
	v_add_f32_e32 v219, v228, v219
	v_add_f32_e32 v219, v229, v219
	v_add_f32_e32 v219, v230, v219
	v_add_f32_e32 v219, v231, v219
	v_add_f32_e32 v219, v232, v219
	v_add_f32_e32 v219, v221, v219
	v_add_f32_e32 v219, v222, v219
	v_add_f32_e32 v219, v223, v219
	v_add_f32_e32 v219, v224, v219
	v_add_f32_e32 v219, v225, v219
	v_mfma_f32_32x32x16_bf16 v[64:79], v[240:243], v[98:101], v[64:79]
	s_cmp_ge_u32 s30, s29
	s_cselect_b64 s[22:23], -1, 0
	s_and_b64 vcc, exec, s[22:23]
	s_cbranch_vccnz .Lap_skipaddr
	v_add_co_u32_e32 v130, vcc, 0x48888000, v188
	s_nop 1
	v_addc_co_u32_e32 v131, vcc, 0, v189, vcc
	v_add_co_u32_e32 v134, vcc, 0x48888000, v186
	s_nop 1
	v_addc_co_u32_e32 v135, vcc, 0, v187, vcc
	v_add_co_u32_e32 v138, vcc, 0x48048000, v188
	s_nop 1
	v_addc_co_u32_e32 v139, vcc, 0, v189, vcc
	v_add_co_u32_e32 v142, vcc, 0x48048000, v186
	s_nop 1
	v_addc_co_u32_e32 v143, vcc, 0, v187, vcc

; __global__ void __launch_bounds__(NTHREADS, 2) mega_fwd(Params p0) {
	.amdhsa_kernel _Z8mega_fwd6Params
		.amdhsa_group_segment_fixed_size 0
		.amdhsa_private_segment_fixed_size 0
		.amdhsa_kernarg_size 416
		.amdhsa_user_sgpr_count 2
		.amdhsa_user_sgpr_dispatch_ptr 0
		.amdhsa_user_sgpr_queue_ptr 0
		.amdhsa_user_sgpr_kernarg_segment_ptr 1
		.amdhsa_user_sgpr_dispatch_id 0
		.amdhsa_user_sgpr_kernarg_preload_length 0
		.amdhsa_user_sgpr_kernarg_preload_offset 0
		.amdhsa_user_sgpr_private_segment_size 0
		.amdhsa_uses_dynamic_stack 0
		.amdhsa_enable_private_segment 0
		.amdhsa_system_sgpr_workgroup_id_x 1
		.amdhsa_system_sgpr_workgroup_id_y 0
		.amdhsa_system_sgpr_workgroup_id_z 0
		.amdhsa_system_sgpr_workgroup_info 0
		.amdhsa_system_vgpr_workitem_id 2
		.amdhsa_next_free_vgpr 256
		.amdhsa_next_free_sgpr 100
		.amdhsa_accum_offset 256
		.amdhsa_reserve_vcc 1
		.amdhsa_float_round_mode_32 0
		.amdhsa_float_round_mode_16_64 0
		.amdhsa_float_denorm_mode_32 3
		.amdhsa_float_denorm_mode_16_64 3
		.amdhsa_dx10_clamp 1
		.amdhsa_ieee_mode 1
		.amdhsa_fp16_overflow 0
		.amdhsa_tg_split 0
		.amdhsa_exception_fp_ieee_invalid_op 0
		.amdhsa_exception_fp_denorm_src 0
		.amdhsa_exception_fp_ieee_div_zero 0
		.amdhsa_exception_fp_ieee_overflow 0
		.amdhsa_exception_fp_ieee_underflow 0
		.amdhsa_exception_fp_ieee_inexact 0
		.amdhsa_exception_int_div_zero 0
	.end_amdhsa_kernel

; __global__ void __launch_bounds__(NTHREADS, 2) mega_fwd(Params p0) {
amdhsa.kernels:
  - .agpr_count:     0
    .args:
      - .offset:         0
        .size:           160
        .value_kind:     by_value
      - .offset:         160
        .size:           4
        .value_kind:     hidden_block_count_x
      - .offset:         164
        .size:           4
        .value_kind:     hidden_block_count_y
      - .offset:         168
        .size:           4
        .value_kind:     hidden_block_count_z
      - .offset:         172
        .size:           2
        .value_kind:     hidden_group_size_x
      - .offset:         174
        .size:           2
        .value_kind:     hidden_group_size_y
      - .offset:         176
        .size:           2
        .value_kind:     hidden_group_size_z
      - .offset:         178
        .size:           2
        .value_kind:     hidden_remainder_x
      - .offset:         180
        .size:           2
        .value_kind:     hidden_remainder_y
      - .offset:         182
        .size:           2
        .value_kind:     hidden_remainder_z
      - .offset:         200
        .size:           8
        .value_kind:     hidden_global_offset_x
      - .offset:         208
        .size:           8
        .value_kind:     hidden_global_offset_y
      - .offset:         216
        .size:           8
        .value_kind:     hidden_global_offset_z
      - .offset:         224
        .size:           2
        .value_kind:     hidden_grid_dims
      - .offset:         248
        .size:           8
        .value_kind:     hidden_multigrid_sync_arg
      - .offset:         280
        .size:           4
        .value_kind:     hidden_dynamic_lds_size
    .group_segment_fixed_size: 0
    .kernarg_segment_align: 8
    .kernarg_segment_size: 416
    .language:       OpenCL C
    .language_version:
      - 2
      - 0
    .max_flat_workgroup_size: 512
    .name:           _Z8mega_fwd6Params
    .private_segment_fixed_size: 0
    .sgpr_count:     106
    .sgpr_spill_count: 199
    .symbol:         _Z8mega_fwd6Params.kd
    .uniform_work_group_size: 1
    .uses_dynamic_stack: false
    .vgpr_count:     256
    .vgpr_spill_count: 0
    .wavefront_size: 64
